# prologue w_in/w_out transposition loop: header drain removed (stores overlap next item), on top of S5-phase conversion counted waits
# speedup vs baseline: 1.0124x; 1.0063x over previous
; #define GAS __attribute__((address_space(1)))
; __device__ __forceinline__ void tr_load(const TrItem& t, f32x4 (&v)[8], int lane) {
;     const int nblk = t.N / 32, kb = t.item / nblk, nb = t.item % nblk, k0 = 64 * kb, n0 = 32 * nb;
; #pragma unroll
;     for (int i = 0; i < 8; ++i) v[i] = __builtin_nontemporal_load((const GAS f32x4*)(t.W + (size_t)(k0 + 8 * i + (lane >> 3)) * t.N + n0 + 4 * (lane & 7)));
; }
; __device__ __forceinline__ void phase_prologue(const PView& p, LAS unsigned char* lds, int tid, int lane, int wave) {
;     ...
;       for (int l = 0; l < DEPTH; ++l) { TrPair tp;
;           tp.W0 = in_I_WIN + (size_t)l * DM * DIN; tp.T0 = (bf16_t*)(ws + WS_WIN) + (size_t)l * DIN * DM; tp.s0 = nullptr; tp.K0 = DM; tp.N0 = DIN; tp.n0 = I_IN;
;           tp.W1 = in_I_WOUT + (size_t)l * DM * DM; tp.T1 = (bf16_t*)(ws + WS_WOUT) + (size_t)l * DM * DM; tp.s1 = in_I_MNG + l * DM; tp.K1 = DM; tp.N1 = DM; tp.n1 = I_O;
;           tr_run(tp, scr, gw, NGW, lane); } }
.LBB0_40:
	s_and_b64 vcc, exec, s[0:1]
	s_cbranch_vccnz .LBB0_39
	s_mul_i32 s4, s12, 0x1800000
	s_add_u32 s20, s48, s4
	s_addc_u32 s21, s49, 0
	s_mul_i32 s4, s12, 0xc00000
	s_add_u32 s22, s76, s4
	s_addc_u32 s23, s77, 0
	s_lshl_b64 s[4:5], s[12:13], 24
	s_add_u32 s24, s51, s4
	s_addc_u32 s25, s52, s5
	s_lshl_b64 s[4:5], s[12:13], 23
	s_add_u32 s26, s7, s4
	s_addc_u32 s27, s9, s5
	s_lshl_b32 s12, s12, 11
	s_lshl_b64 s[4:5], s[12:13], 2
	s_add_u32 s28, s46, s4
	s_addc_u32 s29, s47, s5
	s_and_b64 s[4:5], s[14:15], exec
	s_cselect_b32 s5, s21, s25
	s_cselect_b32 s4, s20, s24
	v_lshl_add_u64 v[2:3], v[74:75], 2, s[4:5]
	v_lshl_add_u64 v[4:5], v[76:77], 2, s[4:5]
	v_lshl_add_u64 v[2:3], v[2:3], 0, s[16:17]
	v_mov_b32_e32 v91, v73
	v_lshl_add_u64 v[4:5], v[4:5], 0, s[16:17]
	v_lshl_add_u64 v[2:3], v[2:3], 0, v[90:91]
	v_lshl_add_u64 v[4:5], v[4:5], 0, v[90:91]
	global_load_dwordx4 v[58:61], v[2:3], off nt
	global_load_dwordx4 v[62:65], v[4:5], off nt
	v_lshl_add_u64 v[2:3], v[78:79], 2, s[4:5]
	v_lshl_add_u64 v[4:5], v[80:81], 2, s[4:5]
	v_lshl_add_u64 v[2:3], v[2:3], 0, s[16:17]
	v_lshl_add_u64 v[4:5], v[4:5], 0, s[16:17]
	v_lshl_add_u64 v[2:3], v[2:3], 0, v[90:91]
	v_lshl_add_u64 v[4:5], v[4:5], 0, v[90:91]
	global_load_dwordx4 v[50:53], v[2:3], off nt
	global_load_dwordx4 v[54:57], v[4:5], off nt
	v_lshl_add_u64 v[2:3], v[82:83], 2, s[4:5]
	v_lshl_add_u64 v[4:5], v[84:85], 2, s[4:5]
	v_lshl_add_u64 v[2:3], v[2:3], 0, s[16:17]
	v_lshl_add_u64 v[4:5], v[4:5], 0, s[16:17]
	v_lshl_add_u64 v[2:3], v[2:3], 0, v[90:91]
	v_lshl_add_u64 v[4:5], v[4:5], 0, v[90:91]
	global_load_dwordx4 v[10:13], v[2:3], off nt
	global_load_dwordx4 v[14:17], v[4:5], off nt
	v_lshl_add_u64 v[2:3], v[86:87], 2, s[4:5]
	v_lshl_add_u64 v[4:5], v[88:89], 2, s[4:5]
	v_lshl_add_u64 v[2:3], v[2:3], 0, s[16:17]
	v_lshl_add_u64 v[4:5], v[4:5], 0, s[16:17]
	v_lshl_add_u64 v[2:3], v[2:3], 0, v[90:91]
	v_lshl_add_u64 v[4:5], v[4:5], 0, v[90:91]
	global_load_dwordx4 v[6:9], v[2:3], off nt
	s_nop 0
	global_load_dwordx4 v[2:5], v[4:5], off nt
	s_cselect_b32 s41, 0, s29
	s_cselect_b32 s40, 0, s28
	s_cselect_b32 s31, s23, s27
	s_cselect_b32 s30, s22, s26
	s_mov_b32 s12, s6
	s_mov_b32 s57, s54
	s_mov_b32 s42, s53
	s_mov_b32 s56, s54
	s_mov_b32 s55, s53
	s_mov_b64 s[34:35], s[40:41]
	s_mov_b64 s[36:37], s[30:31]
	s_waitcnt vmcnt(0)
	s_branch .LBB0_43

; #define LAS __attribute__((address_space(3)))
; __device__ __forceinline__ TrItem tr_make(const TrPair& p, int it) { TrItem t;
;     if (it < p.n0) { t.W = p.W0; t.WT = p.T0; t.kscale = p.s0; t.K = p.K0; t.N = p.N0; t.item = it; }
;     else { t.W = p.W1; t.WT = p.T1; t.kscale = p.s1; t.K = p.K1; t.N = p.N1; t.item = it - p.n0; }
;     return t; }
; __device__ __forceinline__ void tr_run(const TrPair& p, LAS float* scr, int first, int stride, int lane) {
;     const int total = p.n0 + p.n1;
;     f32x4 vn[8]; TrItem tn;
;     if (first < total) { tn = tr_make(p, first); tr_load(tn, vn, lane); }
;     for (int it = first; it < total; it += stride) { const TrItem tc = tn; f32x4 vc[8];
; #pragma unroll
;         for (int i = 0; i < 8; ++i) vc[i] = vn[i];
;         if (it + stride < total) { tn = tr_make(p, it + stride); tr_load(tn, vn, lane); }
.LBB0_43:
	s_add_i32 s12, s12, s94
	s_cmpk_gt_i32 s12, 0x13ff
	s_cselect_b64 s[38:39], -1, 0
	s_and_b64 vcc, exec, s[38:39]
	v_mov_b32_e32 v33, v5
	v_mov_b32_e32 v32, v4
	v_mov_b32_e32 v31, v3
	v_mov_b32_e32 v30, v2
	v_mov_b32_e32 v49, v9
	v_mov_b32_e32 v48, v8
	v_mov_b32_e32 v47, v7
	v_mov_b32_e32 v46, v6
	v_mov_b32_e32 v29, v17
	v_mov_b32_e32 v28, v16
	v_mov_b32_e32 v27, v15
	v_mov_b32_e32 v26, v14
	v_mov_b32_e32 v45, v13
	v_mov_b32_e32 v44, v12
	v_mov_b32_e32 v43, v11
	v_mov_b32_e32 v42, v10
	v_mov_b32_e32 v25, v57
	v_mov_b32_e32 v24, v56
	v_mov_b32_e32 v23, v55
	v_mov_b32_e32 v22, v54
	v_mov_b32_e32 v41, v53
	v_mov_b32_e32 v40, v52
	v_mov_b32_e32 v39, v51
	v_mov_b32_e32 v38, v50
	v_mov_b32_e32 v21, v65
	v_mov_b32_e32 v20, v64
	v_mov_b32_e32 v19, v63
	v_mov_b32_e32 v18, v62
	v_mov_b32_e32 v37, v61
	v_mov_b32_e32 v36, v60
	v_mov_b32_e32 v35, v59
	v_mov_b32_e32 v34, v58
	s_cbranch_vccnz .LBB0_47
	s_movk_i32 s55, 0xc00
	s_mov_b64 s[34:35], 0
	s_cmpk_lt_i32 s12, 0xc00
	s_mov_b64 s[36:37], s[22:23]
	s_mov_b64 s[4:5], s[20:21]
	s_mov_b32 s56, s12
	s_cbranch_scc1 .LBB0_46
	s_add_i32 s56, s12, 0xfffff400
	s_movk_i32 s55, 0x800
	s_mov_b64 s[34:35], s[28:29]
	s_mov_b64 s[36:37], s[26:27]
	s_mov_b64 s[4:5], s[24:25]
